# S32: S31 + combine_ln2 LN wave sums: 24 ds_bpermute -> exact-xor DPP / permlane swaps
# speedup vs baseline: 1.0034x; 1.0015x over previous
; #define LAS __attribute__((address_space(3)))
; __device__ __forceinline__ void ln_norm_only(f32x4 (&v)[8]) {
;     float s = 0.f;
; #pragma unroll
;     for (int j = 0; j < 8; ++j) s += (v[j][0] + v[j][1]) + (v[j][2] + v[j][3]);
;     const float mean = wave_sum(s) * (1.0f / DM); float q = 0.f;
; #pragma unroll
;     for (int j = 0; j < 8; ++j) { v[j] = v[j] - mean; q += (v[j][0] * v[j][0] + v[j][1] * v[j][1]) + (v[j][2] * v[j][2] + v[j][3] * v[j][3]); }
; __device__ __forceinline__ void combine_ln2(Frame& F, int l, int nrows) {
;     ...
;         const LAS float* g2 = PG2 + brow * DM;
;         asm volatile("" ::: "memory");
;         ln_norm_only(xcur);
.LBB0_2525:
	v_mov_b32_e32 v106, v58
	v_mov_b32_e32 v107, v62
	v_mov_b32_e32 v110, v59
	v_mov_b32_e32 v111, v63
	v_pk_add_f32 v[106:107], v[106:107], v[110:111]
	v_mov_b32_e32 v110, v60
	v_mov_b32_e32 v111, v64
	v_mov_b32_e32 v112, v61
	v_mov_b32_e32 v113, v65
	v_pk_add_f32 v[110:111], v[110:111], v[112:113]
	v_mov_b32_e32 v112, v50
	v_pk_add_f32 v[106:107], v[106:107], v[110:111]
	v_mov_b32_e32 v110, v51
	v_mov_b32_e32 v111, v52
	v_mov_b32_e32 v113, v53
	v_pk_add_f32 v[110:111], v[110:111], v[112:113]
	v_add_f32_e32 v107, 0, v107
	v_pk_add_f32 v[110:111], v[110:111], v[110:111] op_sel_hi:[0,1]
	v_add_f32_e32 v107, v106, v107
	v_add_f32_e32 v113, v46, v47
	v_add_f32_e32 v115, v48, v49
	v_mov_b32_e32 v112, v54
	v_mov_b32_e32 v114, v55
	v_mov_b32_e32 v110, v56
	v_mov_b32_e32 v106, v57
	v_pk_add_f32 v[112:113], v[112:113], v[114:115]
	v_pk_add_f32 v[106:107], v[110:111], v[106:107]
	v_mov_b32_e32 v110, v43
	v_pk_add_f32 v[106:107], v[112:113], v[106:107]
	v_mov_b32_e32 v111, v44
	v_mov_b32_e32 v112, v42
	v_mov_b32_e32 v113, v45
	v_pk_add_f32 v[110:111], v[110:111], v[112:113]
	v_pk_add_f32 v[106:107], v[106:107], v[106:107] op_sel_hi:[0,1]
	v_pk_add_f32 v[110:111], v[110:111], v[110:111] op_sel_hi:[0,1]
	v_add_f32_e32 v113, v38, v39
	v_add_f32_e32 v115, v40, v41
	v_mov_b32_e32 v112, v34
	v_mov_b32_e32 v114, v35
	v_mov_b32_e32 v110, v36
	v_mov_b32_e32 v106, v37
	v_pk_add_f32 v[112:113], v[112:113], v[114:115]
	v_pk_add_f32 v[106:107], v[110:111], v[106:107]
	s_lshl_b32 s9, s9, 11
	v_pk_add_f32 v[106:107], v[112:113], v[106:107]
	s_and_b64 s[0:1], s[10:11], exec
	v_add_f32_e32 v106, v106, v107
	v_and_b32_e32 v107, 64, v185
	v_add_u32_e32 v113, 64, v107
	v_xor_b32_e32 v107, 1, v185
	v_cmp_lt_i32_e32 vcc, v107, v113
	s_cselect_b32 s13, s9, 0x1000
	s_mov_b32 s9, 0xf800000
	v_cndmask_b32_e32 v107, v185, v107, vcc
	v_lshlrev_b32_e32 v107, 2, v107
	s_nop 1
	v_mov_b32_dpp v108, v106 quad_perm:[1,0,3,2] row_mask:0xf bank_mask:0xf
	v_readlane_b32 s16, v249, 0
	v_readlane_b32 s22, v249, 6
	s_waitcnt lgkmcnt(0)
	v_add_f32_e32 v106, v106, v108
	v_xor_b32_e32 v108, 2, v185
	v_cmp_lt_i32_e32 vcc, v108, v113
	v_readlane_b32 s23, v249, 7
	v_readlane_b32 s17, v249, 1
	v_cndmask_b32_e32 v108, v185, v108, vcc
	v_lshlrev_b32_e32 v108, 2, v108
	s_nop 1
	v_mov_b32_dpp v110, v106 quad_perm:[2,3,0,1] row_mask:0xf bank_mask:0xf
	v_readlane_b32 s18, v249, 2
	v_readlane_b32 s19, v249, 3
	v_readlane_b32 s20, v249, 4
	v_readlane_b32 s21, v249, 5
	s_waitcnt lgkmcnt(0)
	v_add_f32_e32 v106, v106, v110
	v_xor_b32_e32 v110, 4, v185
	v_cmp_lt_i32_e32 vcc, v110, v113
	s_nop 1
	v_cndmask_b32_e32 v110, v185, v110, vcc
	v_lshlrev_b32_e32 v110, 2, v110
	s_nop 1
	v_mov_b32_dpp v111, v106 row_half_mirror row_mask:0xf bank_mask:0xf
	s_nop 1
	v_mov_b32_dpp v111, v111 quad_perm:[3,2,1,0] row_mask:0xf bank_mask:0xf
	s_waitcnt lgkmcnt(0)
	v_add_f32_e32 v106, v106, v111
	v_xor_b32_e32 v111, 8, v185
	v_cmp_lt_i32_e32 vcc, v111, v113
	s_nop 1
	v_cndmask_b32_e32 v111, v185, v111, vcc
	v_lshlrev_b32_e32 v111, 2, v111
	s_nop 1
	v_mov_b32_dpp v112, v106 row_ror:8 row_mask:0xf bank_mask:0xf
	s_waitcnt lgkmcnt(0)
	v_add_f32_e32 v106, v106, v112
	v_xor_b32_e32 v112, 16, v185
	v_cmp_lt_i32_e32 vcc, v112, v113
	s_nop 1
	v_cndmask_b32_e32 v112, v185, v112, vcc
	v_lshlrev_b32_e32 v112, 2, v112
	v_mov_b32_e32 v114, v106
	s_nop 1
	v_permlane16_swap_b32_e32 v106, v114
	s_waitcnt lgkmcnt(0)
	v_add_f32_e32 v106, v106, v114
	v_xor_b32_e32 v114, 32, v185
	v_cmp_lt_i32_e32 vcc, v114, v113
	s_nop 1
	v_cndmask_b32_e32 v113, v185, v114, vcc
	v_lshlrev_b32_e32 v113, 2, v113
	v_mov_b32_e32 v114, v106
	s_nop 1
	v_permlane32_swap_b32_e32 v106, v114
	s_waitcnt lgkmcnt(0)
	v_add_f32_e32 v122, v106, v114
	v_fmamk_f32 v63, v122, 0xba000000, v63
	v_fmamk_f32 v59, v122, 0xba000000, v59
	v_fmamk_f32 v65, v122, 0xba000000, v65
	v_fmac_f32_e32 v62, 0xba000000, v122
	v_fmamk_f32 v61, v122, 0xba000000, v61
	v_fmac_f32_e32 v58, 0xba000000, v122
	v_mov_b32_e32 v116, v63
	v_mov_b32_e32 v117, v59
	v_fmamk_f32 v64, v122, 0xba000000, v64
	v_fmamk_f32 v60, v122, 0xba000000, v60
	v_mov_b32_e32 v114, v62
	v_mov_b32_e32 v115, v58
	v_pk_mul_f32 v[116:117], v[116:117], v[116:117]
	v_mov_b32_e32 v118, v65
	v_mov_b32_e32 v119, v61
	v_pk_fma_f32 v[114:115], v[114:115], v[114:115], v[116:117]
	v_mov_b32_e32 v116, v64
	v_mov_b32_e32 v117, v60
	v_pk_mul_f32 v[118:119], v[118:119], v[118:119]
	v_fmamk_f32 v51, v122, 0xba000000, v51
	v_pk_fma_f32 v[116:117], v[116:117], v[116:117], v[118:119]
	v_fmamk_f32 v50, v122, 0xba000000, v50
	v_fmamk_f32 v53, v122, 0xba000000, v53
	v_fmac_f32_e32 v52, 0xba000000, v122
	v_pk_add_f32 v[114:115], v[114:115], v[116:117]
	v_pk_mul_f32 v[116:117], v[52:53], v[52:53]
	v_pk_mul_f32 v[118:119], v[50:51], v[50:51]
	v_fmamk_f32 v46, v122, 0xba000000, v46
	v_pk_mov_b32 v[120:121], v[118:119], v[116:117] op_sel:[1,0]
	v_mov_b32_e32 v119, v117
	v_fmamk_f32 v47, v122, 0xba000000, v47
	v_fmac_f32_e32 v48, 0xba000000, v122
	v_mul_f32_e32 v106, v46, v46
	v_pk_add_f32 v[116:117], v[120:121], v[118:119]
	v_fmamk_f32 v49, v122, 0xba000000, v49
	v_pk_fma_f32 v[118:119], v[46:47], v[46:47], v[106:107] op_sel_hi:[1,1,0]
	v_mul_f32_e32 v106, v48, v48
	v_pk_add_f32 v[114:115], v[114:115], v[114:115] op_sel_hi:[0,1]
	v_pk_add_f32 v[116:117], v[116:117], v[116:117] op_sel_hi:[0,1]
	v_pk_fma_f32 v[120:121], v[48:49], v[48:49], v[106:107] op_sel_hi:[1,1,0]
	v_fmamk_f32 v57, v122, 0xba000000, v57
	v_fmamk_f32 v56, v122, 0xba000000, v56
	v_fmamk_f32 v55, v122, 0xba000000, v55
	v_fmac_f32_e32 v54, 0xba000000, v122
	v_mul_f32_e32 v118, v54, v54
	v_mul_f32_e32 v120, v55, v55
	v_mul_f32_e32 v116, v56, v56
	v_mul_f32_e32 v114, v57, v57
; #define LAS __attribute__((address_space(3)))
; __device__ __forceinline__ void ln_norm_only(f32x4 (&v)[8]) {
;     ...
;     for (int j = 0; j < 8; ++j) { v[j] = v[j] - mean; q += (v[j][0] * v[j][0] + v[j][1] * v[j][1]) + (v[j][2] * v[j][2] + v[j][3] * v[j][3]); }
;     const float rstd = 1.0f / sqrtf(wave_sum(q) * (1.0f / DM) + LN_EPS);
; #pragma unroll
;     for (int j = 0; j < 8; ++j) v[j] = v[j] * rstd;
; }
; __device__ __forceinline__ void combine_ln2(Frame& F, int l, int nrows) {
;     ...
;         ln_norm_only(xcur);
;         asm volatile("" ::: "memory");
; #pragma unroll
;         for (int j = 0; j < 8; ++j) { const int cc = 256 * j + 4 * F.lane;
;             xcur[j] = (xcur[j] * *(const LAS f32x4*)(PLW1 + cc) + *(const LAS f32x4*)(PLB1 + cc)) * ALPHA_RES + *(const LAS f32x4*)(g2 + cc) * moe[j]; }
	v_pk_add_f32 v[118:119], v[118:119], v[120:121]
	v_pk_add_f32 v[114:115], v[116:117], v[114:115]
	v_fmamk_f32 v43, v122, 0xba000000, v43
	v_fmamk_f32 v42, v122, 0xba000000, v42
	v_fmamk_f32 v45, v122, 0xba000000, v45
	v_fmac_f32_e32 v44, 0xba000000, v122
	v_pk_add_f32 v[114:115], v[118:119], v[114:115]
	v_pk_mul_f32 v[116:117], v[44:45], v[44:45]
	v_pk_mul_f32 v[118:119], v[42:43], v[42:43]
	v_fmamk_f32 v38, v122, 0xba000000, v38
	v_pk_mov_b32 v[120:121], v[118:119], v[116:117] op_sel:[1,0]
	v_mov_b32_e32 v119, v117
	v_fmamk_f32 v39, v122, 0xba000000, v39
	v_fmac_f32_e32 v40, 0xba000000, v122
	v_mul_f32_e32 v106, v38, v38
	v_pk_add_f32 v[116:117], v[120:121], v[118:119]
	v_fmamk_f32 v41, v122, 0xba000000, v41
	v_pk_fma_f32 v[118:119], v[38:39], v[38:39], v[106:107] op_sel_hi:[1,1,0]
	v_mul_f32_e32 v106, v40, v40
	v_pk_add_f32 v[114:115], v[114:115], v[114:115] op_sel_hi:[0,1]
	v_pk_add_f32 v[116:117], v[116:117], v[116:117] op_sel_hi:[0,1]
	v_pk_fma_f32 v[120:121], v[40:41], v[40:41], v[106:107] op_sel_hi:[1,1,0]
	v_fmamk_f32 v37, v122, 0xba000000, v37
	v_fmamk_f32 v36, v122, 0xba000000, v36
	v_fmamk_f32 v35, v122, 0xba000000, v35
	v_fmac_f32_e32 v34, 0xba000000, v122
	v_mul_f32_e32 v118, v34, v34
	v_mul_f32_e32 v120, v35, v35
	v_mul_f32_e32 v116, v36, v36
	v_mul_f32_e32 v114, v37, v37
	v_pk_add_f32 v[118:119], v[118:119], v[120:121]
	v_pk_add_f32 v[114:115], v[116:117], v[114:115]
	s_nop 0
	v_pk_add_f32 v[114:115], v[118:119], v[114:115]
	s_nop 0
	v_add_f32_e32 v106, v114, v115
	s_nop 1
	v_mov_b32_dpp v114, v106 quad_perm:[1,0,3,2] row_mask:0xf bank_mask:0xf
	s_waitcnt lgkmcnt(0)
	v_add_f32_e32 v106, v106, v114
	s_nop 1
	v_mov_b32_dpp v114, v106 quad_perm:[2,3,0,1] row_mask:0xf bank_mask:0xf
	s_waitcnt lgkmcnt(0)
	v_add_f32_e32 v106, v106, v114
	s_nop 1
	v_mov_b32_dpp v114, v106 row_half_mirror row_mask:0xf bank_mask:0xf
	s_nop 1
	v_mov_b32_dpp v114, v114 quad_perm:[3,2,1,0] row_mask:0xf bank_mask:0xf
	s_waitcnt lgkmcnt(0)
	v_add_f32_e32 v106, v106, v114
	s_nop 1
	v_mov_b32_dpp v114, v106 row_ror:8 row_mask:0xf bank_mask:0xf
	s_waitcnt lgkmcnt(0)
	v_add_f32_e32 v106, v106, v114
	v_mov_b32_e32 v114, v106
	s_nop 1
	v_permlane16_swap_b32_e32 v106, v114
	s_waitcnt lgkmcnt(0)
	v_add_f32_e32 v106, v106, v114
	v_mov_b32_e32 v114, v106
	s_nop 1
	v_permlane32_swap_b32_e32 v106, v114
	s_waitcnt lgkmcnt(0)
	v_add_f32_e32 v106, v106, v114
	v_fmamk_f32 v106, v106, 0x3a000000, v179
	v_cmp_gt_f32_e32 vcc, s9, v106
	v_mul_f32_e32 v114, 0x4f800000, v106
	s_nop 0
	v_cndmask_b32_e32 v106, v106, v114, vcc
	v_sqrt_f32_e32 v114, v106
	s_nop 0
	v_add_u32_e32 v115, -1, v114
	v_fma_f32 v116, -v115, v114, v106
	v_cmp_ge_f32_e64 s[0:1], 0, v116
	v_add_u32_e32 v116, 1, v114
	s_nop 0
	v_cndmask_b32_e64 v115, v114, v115, s[0:1]
	v_fma_f32 v114, -v116, v114, v106
	v_cmp_lt_f32_e64 s[0:1], 0, v114
	s_nop 1
	v_cndmask_b32_e64 v114, v115, v116, s[0:1]
	v_mul_f32_e32 v115, 0x37800000, v114
	v_cndmask_b32_e32 v114, v114, v115, vcc
	v_cmp_class_f32_e32 vcc, v106, v180
	s_nop 1
	v_cndmask_b32_e32 v106, v114, v106, vcc
	v_div_scale_f32 v114, s[0:1], v106, v106, 1.0
	v_rcp_f32_e32 v115, v114
	s_mov_b32 s0, 0x3fb504f3
	v_fma_f32 v116, -v114, v115, 1.0
	v_fmac_f32_e32 v115, v116, v115
	v_div_scale_f32 v116, vcc, 1.0, v106, 1.0
	v_mul_f32_e32 v117, v116, v115
	v_fma_f32 v118, -v114, v117, v116
	v_fmac_f32_e32 v117, v118, v115
	v_fma_f32 v114, -v114, v117, v116
	v_div_fmas_f32 v114, v114, v115, v117
	v_div_fixup_f32 v106, v114, v106, 1.0
	v_pk_mul_f32 v[114:115], v[62:63], v[106:107] op_sel_hi:[1,0]
	v_pk_mul_f32 v[118:119], v[58:59], v[106:107] op_sel_hi:[1,0]
	v_pk_mul_f32 v[122:123], v[50:51], v[106:107] op_sel_hi:[1,0]
	v_pk_mul_f32 v[124:125], v[52:53], v[106:107] op_sel_hi:[1,0]
	v_pk_mul_f32 v[58:59], v[56:57], v[106:107] op_sel_hi:[1,0]
	v_pk_mul_f32 v[56:57], v[38:39], v[106:107] op_sel_hi:[1,0]
	v_pk_mul_f32 v[62:63], v[40:41], v[106:107] op_sel_hi:[1,0]
	v_pk_mul_f32 v[50:51], v[34:35], v[106:107] op_sel_hi:[1,0]
	v_pk_mul_f32 v[52:53], v[36:37], v[106:107] op_sel_hi:[1,0]
	ds_read_b128 v[34:37], v140
	ds_read_b128 v[38:41], v141
	v_pk_mul_f32 v[116:117], v[64:65], v[106:107] op_sel_hi:[1,0]
	v_pk_mul_f32 v[120:121], v[60:61], v[106:107] op_sel_hi:[1,0]
	v_pk_mul_f32 v[126:127], v[46:47], v[106:107] op_sel_hi:[1,0]
	v_pk_mul_f32 v[128:129], v[48:49], v[106:107] op_sel_hi:[1,0]
	v_pk_mul_f32 v[48:49], v[54:55], v[106:107] op_sel_hi:[1,0]
	v_pk_mul_f32 v[60:61], v[42:43], v[106:107] op_sel_hi:[1,0]
	v_pk_mul_f32 v[64:65], v[44:45], v[106:107] op_sel_hi:[1,0]
	s_waitcnt lgkmcnt(0)
	v_pk_fma_f32 v[36:37], v[36:37], v[116:117], v[40:41]
	v_pk_fma_f32 v[34:35], v[34:35], v[114:115], v[38:39]
	v_lshl_add_u32 v106, s13, 2, v139
	v_pk_mul_f32 v[40:41], v[34:35], s[0:1] op_sel_hi:[1,0]
	v_pk_mul_f32 v[34:35], v[36:37], s[0:1] op_sel_hi:[1,0]
	ds_read_b128 v[36:39], v106
	s_waitcnt lgkmcnt(0)
	v_pk_fma_f32 v[34:35], v[104:105], v[38:39], v[34:35]
	v_pk_fma_f32 v[36:37], v[102:103], v[36:37], v[40:41]
	ds_read_b128 v[38:41], v142
	ds_read_b128 v[42:45], v143
	s_waitcnt lgkmcnt(0)
	v_pk_fma_f32 v[40:41], v[40:41], v[120:121], v[44:45]
	v_pk_fma_f32 v[38:39], v[38:39], v[118:119], v[42:43]
	s_nop 0
	v_pk_mul_f32 v[44:45], v[38:39], s[0:1] op_sel_hi:[1,0]
	v_pk_mul_f32 v[38:39], v[40:41], s[0:1] op_sel_hi:[1,0]
	ds_read_b128 v[40:43], v106 offset:1024
	s_waitcnt lgkmcnt(0)
	v_pk_fma_f32 v[38:39], v[100:101], v[42:43], v[38:39]
	v_pk_fma_f32 v[42:43], v[98:99], v[40:41], v[44:45]
	ds_read_b128 v[44:47], v144
	ds_read_b128 v[98:101], v154
	s_waitcnt lgkmcnt(0)
; #define LAS __attribute__((address_space(3)))
; __device__ __forceinline__ void ln_inplace_lds(f32x4 (&v)[8], const LAS float* w, const LAS float* b, int lane) {
;     float s = 0.f;
; #pragma unroll
;     for (int j = 0; j < 8; ++j) s += (v[j][0] + v[j][1]) + (v[j][2] + v[j][3]);
;     const float mean = wave_sum(s) * (1.0f / DM); float q = 0.f;
; __device__ __forceinline__ void combine_ln2(Frame& F, int l, int nrows) {
;     ...
; #pragma unroll
;         for (int j = 0; j < 8; ++j) { const int cc = 256 * j + 4 * F.lane;
;             xcur[j] = (xcur[j] * *(const LAS f32x4*)(PLW1 + cc) + *(const LAS f32x4*)(PLB1 + cc)) * ALPHA_RES + *(const LAS f32x4*)(g2 + cc) * moe[j]; }
;         asm volatile("" ::: "memory");
;         ln_inplace_lds(xcur, PLW, PLB, F.lane);
	v_pk_fma_f32 v[44:45], v[44:45], v[122:123], v[98:99]
	v_pk_fma_f32 v[40:41], v[46:47], v[124:125], v[100:101]
	v_pk_mul_f32 v[54:55], v[44:45], s[0:1] op_sel_hi:[1,0]
	ds_read_b128 v[44:47], v106 offset:2048
	v_pk_mul_f32 v[40:41], v[40:41], s[0:1] op_sel_hi:[1,0]
	s_waitcnt lgkmcnt(0)
	v_pk_fma_f32 v[44:45], v[94:95], v[44:45], v[54:55]
	v_pk_fma_f32 v[40:41], v[96:97], v[46:47], v[40:41]
	ds_read_b128 v[94:97], v155
	ds_read_b128 v[98:101], v156
	s_waitcnt lgkmcnt(0)
	v_pk_fma_f32 v[46:47], v[96:97], v[128:129], v[100:101]
	v_pk_fma_f32 v[54:55], v[94:95], v[126:127], v[98:99]
	ds_read_b128 v[94:97], v106 offset:3072
	v_pk_mul_f32 v[54:55], v[54:55], s[0:1] op_sel_hi:[1,0]
	v_pk_mul_f32 v[46:47], v[46:47], s[0:1] op_sel_hi:[1,0]
	s_waitcnt lgkmcnt(0)
	v_pk_fma_f32 v[54:55], v[90:91], v[94:95], v[54:55]
	v_pk_fma_f32 v[46:47], v[92:93], v[96:97], v[46:47]
	ds_read_b128 v[90:93], v157
	ds_read_b128 v[94:97], v158
	s_waitcnt lgkmcnt(0)
	v_pk_fma_f32 v[58:59], v[92:93], v[58:59], v[96:97]
	v_pk_fma_f32 v[48:49], v[90:91], v[48:49], v[94:95]
	ds_read_b128 v[90:93], v106 offset:4096
	v_pk_mul_f32 v[94:95], v[48:49], s[0:1] op_sel_hi:[1,0]
	v_pk_mul_f32 v[48:49], v[58:59], s[0:1] op_sel_hi:[1,0]
	s_waitcnt lgkmcnt(0)
	v_pk_fma_f32 v[58:59], v[86:87], v[90:91], v[94:95]
	v_pk_fma_f32 v[48:49], v[88:89], v[92:93], v[48:49]
	ds_read_b128 v[86:89], v159
	ds_read_b128 v[90:93], v160
	s_waitcnt lgkmcnt(0)
	v_pk_fma_f32 v[64:65], v[88:89], v[64:65], v[92:93]
	v_pk_fma_f32 v[60:61], v[86:87], v[60:61], v[90:91]
	ds_read_b128 v[86:89], v106 offset:5120
	v_pk_mul_f32 v[90:91], v[60:61], s[0:1] op_sel_hi:[1,0]
	v_pk_mul_f32 v[60:61], v[64:65], s[0:1] op_sel_hi:[1,0]
	s_waitcnt lgkmcnt(0)
	v_pk_fma_f32 v[64:65], v[82:83], v[86:87], v[90:91]
	v_pk_fma_f32 v[60:61], v[84:85], v[88:89], v[60:61]
	ds_read_b128 v[82:85], v161
	ds_read_b128 v[86:89], v162
	s_waitcnt lgkmcnt(0)
	v_pk_fma_f32 v[62:63], v[84:85], v[62:63], v[88:89]
	v_pk_fma_f32 v[56:57], v[82:83], v[56:57], v[86:87]
	ds_read_b128 v[82:85], v106 offset:6144
	v_pk_mul_f32 v[56:57], v[56:57], s[0:1] op_sel_hi:[1,0]
	v_pk_mul_f32 v[62:63], v[62:63], s[0:1] op_sel_hi:[1,0]
	s_waitcnt lgkmcnt(0)
	v_pk_fma_f32 v[78:79], v[78:79], v[82:83], v[56:57]
	v_pk_fma_f32 v[62:63], v[80:81], v[84:85], v[62:63]
	ds_read_b128 v[80:83], v163
	ds_read_b128 v[84:87], v164
	s_waitcnt lgkmcnt(0)
	v_pk_fma_f32 v[52:53], v[82:83], v[52:53], v[86:87]
	v_pk_fma_f32 v[50:51], v[80:81], v[50:51], v[84:85]
	v_pk_mul_f32 v[80:81], v[52:53], s[0:1] op_sel_hi:[1,0]
	v_pk_mul_f32 v[56:57], v[50:51], s[0:1] op_sel_hi:[1,0]
	ds_read_b128 v[50:53], v106 offset:7168
	s_waitcnt lgkmcnt(0)
	v_pk_fma_f32 v[76:77], v[76:77], v[52:53], v[80:81]
	v_pk_fma_f32 v[74:75], v[74:75], v[50:51], v[56:57]
	v_mov_b32_e32 v50, v42
	v_mov_b32_e32 v51, v36
	v_mov_b32_e32 v52, v43
	v_mov_b32_e32 v53, v37
	v_pk_add_f32 v[50:51], v[50:51], v[52:53]
	v_mov_b32_e32 v52, v38
	v_mov_b32_e32 v53, v34
	v_mov_b32_e32 v56, v39
	v_mov_b32_e32 v57, v35
	v_pk_add_f32 v[52:53], v[52:53], v[56:57]
	v_mov_b32_e32 v56, v44
	v_pk_add_f32 v[50:51], v[50:51], v[52:53]
	v_pk_mov_b32 v[52:53], v[44:45], v[40:41] op_sel:[1,0]
	v_mov_b32_e32 v57, v41
	v_pk_add_f32 v[52:53], v[52:53], v[56:57]
	v_add_f32_e32 v51, 0, v51
	v_pk_add_f32 v[52:53], v[52:53], v[52:53] op_sel_hi:[0,1]
	v_add_f32_e32 v51, v50, v51
	v_add_f32_e32 v57, v54, v55
	v_add_f32_e32 v81, v46, v47
	v_mov_b32_e32 v56, v58
	v_mov_b32_e32 v80, v59
	v_mov_b32_e32 v52, v48
	v_mov_b32_e32 v50, v49
	v_pk_add_f32 v[56:57], v[56:57], v[80:81]
	v_pk_add_f32 v[50:51], v[52:53], v[50:51]
	v_pk_mov_b32 v[52:53], v[64:65], v[60:61] op_sel:[1,0]
	v_pk_add_f32 v[50:51], v[56:57], v[50:51]
	v_mov_b32_e32 v56, v64
	v_mov_b32_e32 v57, v61
	v_pk_add_f32 v[52:53], v[52:53], v[56:57]
	v_pk_add_f32 v[50:51], v[50:51], v[50:51] op_sel_hi:[0,1]
	v_pk_add_f32 v[52:53], v[52:53], v[52:53] op_sel_hi:[0,1]
	v_add_f32_e32 v57, v78, v79
	v_add_f32_e32 v81, v62, v63
	v_mov_b32_e32 v56, v74
	v_mov_b32_e32 v80, v75
	v_mov_b32_e32 v52, v76
	v_mov_b32_e32 v50, v77
	v_pk_add_f32 v[56:57], v[56:57], v[80:81]
	v_pk_add_f32 v[50:51], v[52:53], v[50:51]
	s_nop 0
	v_pk_add_f32 v[50:51], v[56:57], v[50:51]
	s_nop 0
	v_add_f32_e32 v50, v50, v51
	s_nop 1
	v_mov_b32_dpp v51, v50 quad_perm:[1,0,3,2] row_mask:0xf bank_mask:0xf
	s_waitcnt lgkmcnt(0)
	v_add_f32_e32 v50, v50, v51
	s_nop 1
	v_mov_b32_dpp v51, v50 quad_perm:[2,3,0,1] row_mask:0xf bank_mask:0xf
	s_waitcnt lgkmcnt(0)
	v_add_f32_e32 v50, v50, v51
	s_nop 1
	v_mov_b32_dpp v51, v50 row_half_mirror row_mask:0xf bank_mask:0xf
	s_nop 1
	v_mov_b32_dpp v51, v51 quad_perm:[3,2,1,0] row_mask:0xf bank_mask:0xf
	s_waitcnt lgkmcnt(0)
	v_add_f32_e32 v50, v50, v51
	s_nop 1
	v_mov_b32_dpp v51, v50 row_ror:8 row_mask:0xf bank_mask:0xf
	s_waitcnt lgkmcnt(0)
	v_add_f32_e32 v50, v50, v51
	v_mov_b32_e32 v51, v50
	s_nop 1
	v_permlane16_swap_b32_e32 v50, v51
	s_waitcnt lgkmcnt(0)
	v_add_f32_e32 v50, v50, v51
	v_mov_b32_e32 v51, v50
	s_nop 1
	v_permlane32_swap_b32_e32 v50, v51
	s_waitcnt lgkmcnt(0)
; #define LAS __attribute__((address_space(3)))
; __device__ __forceinline__ void ln_inplace_lds(f32x4 (&v)[8], const LAS float* w, const LAS float* b, int lane) {
;     ...
;     const float mean = wave_sum(s) * (1.0f / DM); float q = 0.f;
; #pragma unroll
;     for (int j = 0; j < 8; ++j) { v[j] = v[j] - mean; q += (v[j][0] * v[j][0] + v[j][1] * v[j][1]) + (v[j][2] * v[j][2] + v[j][3] * v[j][3]); }
;     const float rstd = 1.0f / sqrtf(wave_sum(q) * (1.0f / DM) + LN_EPS);
; #pragma unroll
;     for (int j = 0; j < 8; ++j) { const int c = 256 * j + 4 * lane; v[j] = v[j] * rstd * *(const LAS f32x4*)(w + c) + *(const LAS f32x4*)(b + c); }
	v_add_f32_e32 v82, v50, v51
	v_fmamk_f32 v37, v82, 0xba000000, v37
	v_fmamk_f32 v43, v82, 0xba000000, v43
	v_fmamk_f32 v35, v82, 0xba000000, v35
	v_fmac_f32_e32 v36, 0xba000000, v82
	v_fmamk_f32 v39, v82, 0xba000000, v39
	v_fmac_f32_e32 v42, 0xba000000, v82
	v_mov_b32_e32 v52, v37
	v_mov_b32_e32 v53, v43
	v_fmac_f32_e32 v34, 0xba000000, v82
	v_fmac_f32_e32 v38, 0xba000000, v82
	v_mov_b32_e32 v50, v36
	v_mov_b32_e32 v51, v42
	v_pk_mul_f32 v[52:53], v[52:53], v[52:53]
	v_mov_b32_e32 v56, v35
	v_mov_b32_e32 v57, v39
	v_pk_fma_f32 v[50:51], v[50:51], v[50:51], v[52:53]
	v_mov_b32_e32 v52, v34
	v_mov_b32_e32 v53, v38
	v_pk_mul_f32 v[56:57], v[56:57], v[56:57]
	v_fmamk_f32 v45, v82, 0xba000000, v45
	v_pk_fma_f32 v[52:53], v[52:53], v[52:53], v[56:57]
	v_fmac_f32_e32 v44, 0xba000000, v82
	v_pk_add_f32 v[50:51], v[50:51], v[52:53]
	v_fmamk_f32 v41, v82, 0xba000000, v41
	v_fmac_f32_e32 v40, 0xba000000, v82
	v_pk_add_f32 v[50:51], v[50:51], v[50:51] op_sel_hi:[0,1]
	v_pk_mul_f32 v[52:53], v[40:41], v[40:41]
	v_pk_mul_f32 v[56:57], v[44:45], v[44:45]
	v_fmac_f32_e32 v54, 0xba000000, v82
	v_pk_mov_b32 v[80:81], v[56:57], v[52:53] op_sel:[1,0]
	v_mov_b32_e32 v57, v53
	v_fmamk_f32 v55, v82, 0xba000000, v55
	v_fmac_f32_e32 v46, 0xba000000, v82
	v_mul_f32_e32 v50, v54, v54
	v_pk_add_f32 v[52:53], v[80:81], v[56:57]
	v_fmamk_f32 v47, v82, 0xba000000, v47
	v_pk_fma_f32 v[56:57], v[54:55], v[54:55], v[50:51] op_sel_hi:[1,1,0]
	v_mul_f32_e32 v50, v46, v46
	v_pk_add_f32 v[52:53], v[52:53], v[52:53] op_sel_hi:[0,1]
	v_pk_fma_f32 v[80:81], v[46:47], v[46:47], v[50:51] op_sel_hi:[1,1,0]
	v_fmamk_f32 v49, v82, 0xba000000, v49
	v_fmac_f32_e32 v48, 0xba000000, v82
	v_fmamk_f32 v59, v82, 0xba000000, v59
	v_fmac_f32_e32 v58, 0xba000000, v82
	v_mul_f32_e32 v56, v58, v58
	v_mul_f32_e32 v80, v59, v59
	v_mul_f32_e32 v52, v48, v48
	v_mul_f32_e32 v50, v49, v49
	v_pk_add_f32 v[56:57], v[56:57], v[80:81]
	v_pk_add_f32 v[50:51], v[52:53], v[50:51]
	v_fmamk_f32 v65, v82, 0xba000000, v65
	v_pk_add_f32 v[50:51], v[56:57], v[50:51]
	v_fmac_f32_e32 v64, 0xba000000, v82
	v_fmamk_f32 v61, v82, 0xba000000, v61
	v_fmac_f32_e32 v60, 0xba000000, v82
	v_pk_add_f32 v[50:51], v[50:51], v[50:51] op_sel_hi:[0,1]
	v_pk_mul_f32 v[52:53], v[60:61], v[60:61]
	v_pk_mul_f32 v[56:57], v[64:65], v[64:65]
	v_fmac_f32_e32 v78, 0xba000000, v82
	v_pk_mov_b32 v[80:81], v[56:57], v[52:53] op_sel:[1,0]
	v_mov_b32_e32 v57, v53
	v_fmamk_f32 v79, v82, 0xba000000, v79
	v_fmac_f32_e32 v62, 0xba000000, v82
	v_mul_f32_e32 v50, v78, v78
	v_pk_add_f32 v[52:53], v[80:81], v[56:57]
	v_fmamk_f32 v63, v82, 0xba000000, v63
	v_pk_fma_f32 v[56:57], v[78:79], v[78:79], v[50:51] op_sel_hi:[1,1,0]
	v_mul_f32_e32 v50, v62, v62
	v_pk_add_f32 v[52:53], v[52:53], v[52:53] op_sel_hi:[0,1]
	v_pk_fma_f32 v[80:81], v[62:63], v[62:63], v[50:51] op_sel_hi:[1,1,0]
	v_fmamk_f32 v77, v82, 0xba000000, v77
	v_fmac_f32_e32 v76, 0xba000000, v82
	v_fmamk_f32 v75, v82, 0xba000000, v75
	v_fmac_f32_e32 v74, 0xba000000, v82
	v_mul_f32_e32 v56, v74, v74
	v_mul_f32_e32 v80, v75, v75
	v_mul_f32_e32 v52, v76, v76
	v_mul_f32_e32 v50, v77, v77
	v_pk_add_f32 v[56:57], v[56:57], v[80:81]
	v_pk_add_f32 v[50:51], v[52:53], v[50:51]
	s_nop 0
	v_pk_add_f32 v[50:51], v[56:57], v[50:51]
	s_nop 0
	v_add_f32_e32 v50, v50, v51
	s_nop 1
	v_mov_b32_dpp v51, v50 quad_perm:[1,0,3,2] row_mask:0xf bank_mask:0xf
	s_waitcnt lgkmcnt(0)
	v_add_f32_e32 v50, v50, v51
	s_nop 1
	v_mov_b32_dpp v51, v50 quad_perm:[2,3,0,1] row_mask:0xf bank_mask:0xf
	s_waitcnt lgkmcnt(0)
	v_add_f32_e32 v50, v50, v51
	s_nop 1
	v_mov_b32_dpp v51, v50 row_half_mirror row_mask:0xf bank_mask:0xf
	s_nop 1
	v_mov_b32_dpp v51, v51 quad_perm:[3,2,1,0] row_mask:0xf bank_mask:0xf
	s_waitcnt lgkmcnt(0)
	v_add_f32_e32 v50, v50, v51
	s_nop 1
	v_mov_b32_dpp v51, v50 row_ror:8 row_mask:0xf bank_mask:0xf
	s_waitcnt lgkmcnt(0)
	v_add_f32_e32 v50, v50, v51
	v_mov_b32_e32 v51, v50
	s_nop 1
	v_permlane16_swap_b32_e32 v50, v51
	s_waitcnt lgkmcnt(0)
	v_add_f32_e32 v50, v50, v51
	v_mov_b32_e32 v51, v50
	s_nop 1
	v_permlane32_swap_b32_e32 v50, v51
	s_waitcnt lgkmcnt(0)
	v_add_f32_e32 v50, v50, v51
	v_fmamk_f32 v50, v50, 0x3a000000, v179
	v_cmp_gt_f32_e32 vcc, s9, v50
	v_mul_f32_e32 v51, 0x4f800000, v50
	s_ashr_i32 s9, s8, 31
	v_cndmask_b32_e32 v50, v50, v51, vcc
	v_sqrt_f32_e32 v51, v50
	s_nop 0
	v_add_u32_e32 v52, -1, v51
	v_fma_f32 v53, -v52, v51, v50
	v_cmp_ge_f32_e64 s[0:1], 0, v53
	v_add_u32_e32 v53, 1, v51
	s_nop 0
	v_cndmask_b32_e64 v52, v51, v52, s[0:1]
	v_fma_f32 v51, -v53, v51, v50
	v_cmp_lt_f32_e64 s[0:1], 0, v51
	s_nop 1
	v_cndmask_b32_e64 v51, v52, v53, s[0:1]
	v_mul_f32_e32 v52, 0x37800000, v51
	v_cndmask_b32_e32 v51, v51, v52, vcc
	v_cmp_class_f32_e32 vcc, v50, v180
	s_and_b64 s[0:1], s[10:11], exec
	v_readlane_b32 s10, v251, 30
	v_cndmask_b32_e32 v50, v51, v50, vcc
	v_div_scale_f32 v51, s[0:1], v50, v50, 1.0
	v_rcp_f32_e32 v52, v51
	s_cselect_b32 s1, s9, 0
	s_cselect_b32 s0, s8, s5
	v_readlane_b32 s5, v251, 31
	v_fma_f32 v53, -v51, v52, 1.0
	v_fmac_f32_e32 v52, v53, v52
	v_div_scale_f32 v53, vcc, 1.0, v50, 1.0
	v_mul_f32_e32 v56, v53, v52
	v_fma_f32 v57, -v51, v56, v53
	v_fmac_f32_e32 v56, v57, v52
	v_fma_f32 v51, -v51, v56, v53
	v_div_fmas_f32 v51, v51, v52, v56
	v_div_fixup_f32 v80, v51, v50, 1.0
	v_pk_mul_f32 v[56:57], v[36:37], v[80:81] op_sel_hi:[1,0]
	v_pk_mul_f32 v[82:83], v[34:35], v[80:81] op_sel_hi:[1,0]
	ds_read_b128 v[34:37], v139 offset:24576
	ds_read_b128 v[50:53], v139 offset:32768
	v_pk_mul_f32 v[42:43], v[42:43], v[80:81] op_sel_hi:[1,0]
	v_pk_mul_f32 v[38:39], v[38:39], v[80:81] op_sel_hi:[1,0]
	v_pk_mul_f32 v[46:47], v[46:47], v[80:81] op_sel_hi:[1,0]
	v_pk_mul_f32 v[58:59], v[58:59], v[80:81] op_sel_hi:[1,0]
	s_waitcnt lgkmcnt(0)
; #define LAS __attribute__((address_space(3)))
; __device__ __forceinline__ void ln_inplace_lds(f32x4 (&v)[8], const LAS float* w, const LAS float* b, int lane) {
;     ...
;     const float rstd = 1.0f / sqrtf(wave_sum(q) * (1.0f / DM) + LN_EPS);
; #pragma unroll
;     for (int j = 0; j < 8; ++j) { const int c = 256 * j + 4 * lane; v[j] = v[j] * rstd * *(const LAS f32x4*)(w + c) + *(const LAS f32x4*)(b + c); }
; __device__ __forceinline__ void combine_ln2(Frame& F, int l, int nrows) {
;     ...
;         float* orow = lat ? F.out + (size_t)row * DM : (float*)(F.ws + WS_R2C) + (size_t)(row - NLAT) * DM;
; #pragma unroll
;         for (int j = 0; j < 8; ++j) *(f32x4*)(orow + 256 * j + 4 * F.lane) = xcur[j];
	v_pk_fma_f32 v[36:37], v[36:37], v[82:83], v[52:53]
	v_pk_fma_f32 v[34:35], v[34:35], v[56:57], v[50:51]
	ds_read_b128 v[50:53], v139 offset:25600
	ds_read_b128 v[82:85], v139 offset:33792
	v_pk_mul_f32 v[56:57], v[44:45], v[80:81] op_sel_hi:[1,0]
	v_pk_mul_f32 v[64:65], v[64:65], v[80:81] op_sel_hi:[1,0]
	v_pk_mul_f32 v[78:79], v[78:79], v[80:81] op_sel_hi:[1,0]
	s_cselect_b32 s5, s23, s5
	s_waitcnt lgkmcnt(0)
	v_pk_fma_f32 v[52:53], v[52:53], v[38:39], v[84:85]
	v_pk_fma_f32 v[50:51], v[50:51], v[42:43], v[82:83]
	v_pk_mul_f32 v[82:83], v[40:41], v[80:81] op_sel_hi:[1,0]
	ds_read_b128 v[38:41], v139 offset:26624
	ds_read_b128 v[42:45], v139 offset:34816
	s_cselect_b32 s10, s22, s10
	s_lshl_b64 s[0:1], s[0:1], 13
	s_add_u32 s0, s10, s0
	s_addc_u32 s1, s5, s1
	s_waitcnt lgkmcnt(0)
	v_pk_fma_f32 v[40:41], v[40:41], v[82:83], v[44:45]
	v_pk_fma_f32 v[38:39], v[38:39], v[56:57], v[42:43]
	v_pk_mul_f32 v[82:83], v[54:55], v[80:81] op_sel_hi:[1,0]
	ds_read_b128 v[42:45], v139 offset:27648
	ds_read_b128 v[54:57], v139 offset:35840
	s_waitcnt lgkmcnt(0)
	v_pk_fma_f32 v[56:57], v[44:45], v[46:47], v[56:57]
	v_pk_fma_f32 v[54:55], v[42:43], v[82:83], v[54:55]
	v_pk_mul_f32 v[82:83], v[48:49], v[80:81] op_sel_hi:[1,0]
	ds_read_b128 v[42:45], v139 offset:28672
	ds_read_b128 v[46:49], v139 offset:36864
	s_waitcnt lgkmcnt(0)
	v_pk_fma_f32 v[44:45], v[44:45], v[82:83], v[48:49]
	v_pk_fma_f32 v[42:43], v[42:43], v[58:59], v[46:47]
	v_pk_mul_f32 v[82:83], v[60:61], v[80:81] op_sel_hi:[1,0]
	ds_read_b128 v[46:49], v139 offset:29696
	ds_read_b128 v[58:61], v139 offset:37888
	s_waitcnt lgkmcnt(0)
	v_pk_fma_f32 v[60:61], v[48:49], v[82:83], v[60:61]
	v_pk_fma_f32 v[58:59], v[46:47], v[64:65], v[58:59]
	v_pk_mul_f32 v[82:83], v[62:63], v[80:81] op_sel_hi:[1,0]
	ds_read_b128 v[46:49], v139 offset:30720
	ds_read_b128 v[62:65], v139 offset:38912
	s_waitcnt lgkmcnt(0)
	v_pk_fma_f32 v[48:49], v[48:49], v[82:83], v[64:65]
	v_pk_fma_f32 v[46:47], v[46:47], v[78:79], v[62:63]
	v_pk_mul_f32 v[78:79], v[74:75], v[80:81] op_sel_hi:[1,0]
	v_pk_mul_f32 v[80:81], v[76:77], v[80:81] op_sel_hi:[1,0]
	ds_read_b128 v[62:65], v139 offset:31744
	ds_read_b128 v[74:77], v139 offset:39936
	global_store_dwordx4 v146, v[34:37], s[0:1]
	global_store_dwordx4 v146, v[50:53], s[0:1] offset:1024
	global_store_dwordx4 v146, v[38:41], s[0:1] offset:2048
	global_store_dwordx4 v146, v[54:57], s[0:1] offset:3072
	s_waitcnt lgkmcnt(0)
	v_pk_fma_f32 v[62:63], v[62:63], v[78:79], v[74:75]
	v_lshl_add_u64 v[74:75], s[0:1], 0, v[146:147]
	v_add_co_u32_e32 v74, vcc, 0x1000, v74
	v_readlane_b32 s0, v254, 21
	s_nop 0
	v_addc_co_u32_e32 v75, vcc, 0, v75, vcc
	v_readlane_b32 s1, v254, 22
	v_pk_fma_f32 v[64:65], v[64:65], v[80:81], v[76:77]
	s_andn2_b64 vcc, exec, s[0:1]
	global_store_dwordx4 v[74:75], v[42:45], off
	global_store_dwordx4 v[74:75], v[58:61], off offset:1024
	global_store_dwordx4 v[74:75], v[46:49], off offset:2048
	global_store_dwordx4 v[74:75], v[62:65], off offset:3072
	s_cbranch_vccnz .LBB0_2511
; #define LAS __attribute__((address_space(3)))
; __device__ __forceinline__ unsigned pk2(float lo, float hi) { return f2bf(lo) | (f2bf(hi) << 16); }
; __device__ __forceinline__ void store_mod_bf16_lds(bf16* orow, const f32x4 (&v)[8], const LAS float* sh, const LAS float* sc1p, int lane) {
; #pragma unroll
;     for (int j = 0; j < 8; ++j) { const int c = 256 * j + 4 * lane; const f32x4 s1 = *(const LAS f32x4*)(sc1p + c), s0 = *(const LAS f32x4*)(sh + c);
;         const f32x4 h = v[j] * s1 + s0; v2u w; w.x = pk2(h[0], h[1]); w.y = pk2(h[2], h[3]); *(v2u*)(orow + c) = w; }
; }
; __device__ __forceinline__ void combine_ln2(Frame& F, int l, int nrows) {
;     ...
;         if (l + 1 < DEPTH) store_mod_bf16_lds((bf16*)(F.ws + WS_XM) + (size_t)row * DM, xcur, PSH + brow * DM, PSC + brow * DM, F.lane);
	v_lshl_add_u32 v92, s13, 2, v165
	ds_read_b128 v[74:77], v106 offset:40960
	ds_read_b128 v[78:81], v92
	ds_read_b128 v[82:85], v106 offset:41984
	ds_read_b128 v[86:89], v92 offset:1024
	s_lshl_b64 s[0:1], s[8:9], 12
	v_lshl_add_u64 v[90:91], v[72:73], 0, s[0:1]
	s_waitcnt lgkmcnt(2)
	v_pk_fma_f32 v[34:35], v[34:35], v[78:79], v[74:75]
	s_nop 0
	v_bfe_u32 v74, v34, 16, 1
	v_add3_u32 v34, v34, v74, s70
	v_bfe_u32 v74, v35, 16, 1
	v_pk_fma_f32 v[36:37], v[36:37], v[80:81], v[76:77]
	v_lshrrev_b32_e32 v34, 16, v34
	v_add3_u32 v35, v35, v74, s70
	v_and_or_b32 v34, v35, s33, v34
	v_bfe_u32 v35, v36, 16, 1
	v_add3_u32 v35, v36, v35, s70
	v_bfe_u32 v36, v37, 16, 1
	v_lshrrev_b32_e32 v35, 16, v35
	v_add3_u32 v36, v37, v36, s70
	v_and_or_b32 v35, v36, s33, v35
	s_waitcnt lgkmcnt(0)
	v_pk_fma_f32 v[36:37], v[50:51], v[86:87], v[82:83]
	global_store_dwordx2 v[90:91], v[34:35], off
	v_bfe_u32 v50, v36, 16, 1
	v_add3_u32 v36, v36, v50, s70
	v_bfe_u32 v50, v37, 16, 1
	v_pk_fma_f32 v[34:35], v[52:53], v[88:89], v[84:85]
	v_lshrrev_b32_e32 v36, 16, v36
	v_add3_u32 v37, v37, v50, s70
	v_and_or_b32 v74, v37, s33, v36
	v_bfe_u32 v36, v34, 16, 1
	v_add3_u32 v34, v34, v36, s70
	v_lshrrev_b32_e32 v75, 16, v34
	v_bfe_u32 v34, v35, 16, 1
	v_add3_u32 v76, v35, v34, s70
	ds_read_b128 v[34:37], v92 offset:2048
	ds_read_b128 v[50:53], v106 offset:43008
	v_and_or_b32 v75, v76, s33, v75
	global_store_dwordx2 v[90:91], v[74:75], off offset:512
	ds_read_b128 v[74:77], v92 offset:3072
	ds_read_b128 v[78:81], v106 offset:44032
	s_waitcnt lgkmcnt(2)
	v_pk_fma_f32 v[34:35], v[38:39], v[34:35], v[50:51]
	s_nop 0
	v_bfe_u32 v38, v34, 16, 1
	v_add3_u32 v34, v34, v38, s70
	v_bfe_u32 v38, v35, 16, 1
	v_pk_fma_f32 v[36:37], v[40:41], v[36:37], v[52:53]
	v_lshrrev_b32_e32 v34, 16, v34
	v_add3_u32 v35, v35, v38, s70
	v_and_or_b32 v34, v35, s33, v34
	v_bfe_u32 v35, v36, 16, 1
	v_add3_u32 v35, v36, v35, s70
	v_bfe_u32 v36, v37, 16, 1
	v_lshrrev_b32_e32 v35, 16, v35
	v_add3_u32 v36, v37, v36, s70
	v_and_or_b32 v35, v36, s33, v35
	s_waitcnt lgkmcnt(0)
	v_pk_fma_f32 v[36:37], v[54:55], v[74:75], v[78:79]
	global_store_dwordx2 v[90:91], v[34:35], off offset:1024
	v_bfe_u32 v38, v36, 16, 1
	v_add3_u32 v36, v36, v38, s70
	v_bfe_u32 v38, v37, 16, 1
	v_pk_fma_f32 v[34:35], v[56:57], v[76:77], v[80:81]
	v_lshrrev_b32_e32 v36, 16, v36
	v_add3_u32 v37, v37, v38, s70
	v_and_or_b32 v50, v37, s33, v36
	v_bfe_u32 v36, v34, 16, 1
	v_add3_u32 v34, v34, v36, s70
	v_lshrrev_b32_e32 v51, 16, v34
	v_bfe_u32 v34, v35, 16, 1
	v_add3_u32 v52, v35, v34, s70
	ds_read_b128 v[34:37], v92 offset:4096
	ds_read_b128 v[38:41], v106 offset:45056
	v_and_or_b32 v51, v52, s33, v51
	global_store_dwordx2 v[90:91], v[50:51], off offset:1536
	ds_read_b128 v[50:53], v92 offset:5120
	ds_read_b128 v[54:57], v106 offset:46080
	s_waitcnt lgkmcnt(2)
	v_pk_fma_f32 v[34:35], v[42:43], v[34:35], v[38:39]
	s_nop 0
	v_bfe_u32 v38, v34, 16, 1
	v_add3_u32 v34, v34, v38, s70
	v_bfe_u32 v38, v35, 16, 1
	v_pk_fma_f32 v[36:37], v[44:45], v[36:37], v[40:41]
	v_lshrrev_b32_e32 v34, 16, v34
	v_add3_u32 v35, v35, v38, s70
	v_and_or_b32 v34, v35, s33, v34
	v_bfe_u32 v35, v36, 16, 1
	v_add3_u32 v35, v36, v35, s70
	v_bfe_u32 v36, v37, 16, 1
	v_lshrrev_b32_e32 v35, 16, v35
	v_add3_u32 v36, v37, v36, s70
	v_and_or_b32 v35, v36, s33, v35
	s_waitcnt lgkmcnt(0)
	v_pk_fma_f32 v[36:37], v[58:59], v[50:51], v[54:55]
	global_store_dwordx2 v[90:91], v[34:35], off offset:2048
	v_bfe_u32 v38, v36, 16, 1
	v_add3_u32 v36, v36, v38, s70
	v_bfe_u32 v38, v37, 16, 1
	v_pk_fma_f32 v[34:35], v[60:61], v[52:53], v[56:57]
	v_lshrrev_b32_e32 v36, 16, v36
	v_add3_u32 v37, v37, v38, s70
	v_and_or_b32 v42, v37, s33, v36
	v_bfe_u32 v36, v34, 16, 1
	v_add3_u32 v34, v34, v36, s70
	v_lshrrev_b32_e32 v43, 16, v34
	v_bfe_u32 v34, v35, 16, 1
	v_add3_u32 v44, v35, v34, s70
	ds_read_b128 v[34:37], v92 offset:6144
	ds_read_b128 v[38:41], v106 offset:47104
	v_and_or_b32 v43, v44, s33, v43
	global_store_dwordx2 v[90:91], v[42:43], off offset:2560
	ds_read_b128 v[42:45], v92 offset:7168
	ds_read_b128 v[50:53], v106 offset:48128
	s_waitcnt lgkmcnt(2)
	v_pk_fma_f32 v[34:35], v[46:47], v[34:35], v[38:39]
	s_nop 0
	v_bfe_u32 v38, v34, 16, 1
	v_add3_u32 v34, v34, v38, s70
	v_bfe_u32 v38, v35, 16, 1
	v_pk_fma_f32 v[36:37], v[48:49], v[36:37], v[40:41]
	v_lshrrev_b32_e32 v34, 16, v34
	v_add3_u32 v35, v35, v38, s70
	v_and_or_b32 v34, v35, s33, v34
	v_bfe_u32 v35, v36, 16, 1
	v_add3_u32 v35, v36, v35, s70
	v_bfe_u32 v36, v37, 16, 1
	v_lshrrev_b32_e32 v35, 16, v35
	v_add3_u32 v36, v37, v36, s70
	v_and_or_b32 v35, v36, s33, v35
	s_waitcnt lgkmcnt(0)
	v_pk_fma_f32 v[36:37], v[62:63], v[42:43], v[50:51]
	global_store_dwordx2 v[90:91], v[34:35], off offset:3072
	v_bfe_u32 v38, v36, 16, 1
	v_add3_u32 v36, v36, v38, s70
	v_bfe_u32 v38, v37, 16, 1
	v_pk_fma_f32 v[34:35], v[64:65], v[44:45], v[52:53]
	v_lshrrev_b32_e32 v36, 16, v36
	v_add3_u32 v37, v37, v38, s70
	v_and_or_b32 v36, v37, s33, v36
	v_bfe_u32 v37, v34, 16, 1
	v_add3_u32 v34, v34, v37, s70
	v_bfe_u32 v37, v35, 16, 1
	v_lshrrev_b32_e32 v34, 16, v34
	v_add3_u32 v35, v35, v37, s70
	v_and_or_b32 v37, v35, s33, v34
	global_store_dwordx2 v[90:91], v[36:37], off offset:3584
	s_branch .LBB0_2511
